# SWA phase rewritten by hand on 16x16x32 MFMA: bias+mask as MFMA C operand, exact row max, P as B operand of P.V, K/V + 8 heads' bias tables staged once per kv head, next Q prefetched
# speedup vs baseline: 1.0175x; 1.0135x over previous
; #define LAS __attribute__((address_space(3)))
; template <bool MLA> __device__ __forceinline__ void attn_unit(const AttnP& P, int b, int hh, int qb, LAS char* lds) {
;     ...
;     const int tid = threadIdx.x, wid = __builtin_amdgcn_readfirstlane(tid >> 6), lane = tid & 63, r32 = lane & 31, hi = lane >> 5;
;     LAS char* V_lds = lds; LAS char* K_lds = lds + 2 * VBYTES;
;     LAS float* ws = (LAS float*)(lds + 2 * VBYTES + 2 * KBYTES) + wid * 64; LAS float* li_l = ws; LAS float* al_l = ws + 32;
;     LAS float* bias_l = (LAS float*)(lds + 2 * VBYTES + 2 * KBYTES + 2048);
;     const int q0 = qb * 256; const size_t rowbase = (size_t)b * SEQ;
;     const int jt0 = MLA ? 0 : (q0 == 0 ? 0 : -2);
;     const int NT = MLA ? 4 * qb + 4 : 4 - jt0;
;     const int kbase0 = MLA ? 0 : q0 + 64 * jt0;
;     const int qlo = q0 + wid * 32, qm = qlo + r32 - 4 * hi;
;     bf16x8 qr[NQF];
;     const size_t qrow = rowbase + qlo + r32;
;     if constexpr (MLA) {
; #pragma unroll
;         for (int d0 = 0; d0 < 8; ++d0) qr[d0] = *(const bf16x8*)(P.QN + qrow * 2048 + hh * 128 + d0 * 16 + hi * 8);
; #pragma unroll
;         for (int d0 = 0; d0 < 4; ++d0) qr[8 + d0] = *(const bf16x8*)(P.QR + qrow * 1024 + hh * 64 + d0 * 16 + hi * 8);
;     } else {
; #pragma unroll
;         for (int d0 = 0; d0 < 4; ++d0) qr[d0] = *(const bf16x8*)(P.QS + qrow * 2048 + hh * 64 + d0 * 16 + hi * 8);
;         if (tid < 128) bias_l[tid] = P.rel[(int)T5B[tid] * 32 + hh] * (1.0f / SCALE);
;     }
;     bf16x8 sk0, sv0;
;     const int sr8 = tid >> 3, ch8 = tid & 7;
;     const bf16_t* Kg; const bf16_t* Vg; const bf16_t* Rg = nullptr;
;     unsigned okA = 0, okB = 0, orp = 0, ovA = 0, ovB = 0;
;     if constexpr (MLA) {
;         Kg = P.KN + rowbase * 2048 + hh * 128; Vg = P.V + rowbase * 2048 + hh * 128; Rg = P.KR + rowbase * 64;
;         { const int rA = 4 * wid + (lane >> 4), rB = rA + 32, cp = lane & 15; okA = (unsigned)(rA * 2048 + ((cp ^ (rA & 7)) << 3)); okB = (unsigned)(rB * 2048 + ((cp ^ (rB & 7)) << 3)); }
;         { const int rr = 8 * wid + (lane >> 3), cp = lane & 7; orp = (unsigned)(rr * 64 + ((cp ^ (rr & 7)) << 3)); }
;         { const int stA = 2 * wid + (lane >> 5), stB = stA + 16; const int kl = (lane & 31) >> 2, c8 = 8 * (lane & 3);
;           const int kkA = (stA >> 2) * 8 + kl, kkB = (stB >> 2) * 8 + kl;
.LBB0_597:
	v_readlane_b32 s64, v253, 0
	s_cmpk_gt_i32 s2, 0xfff
	v_readlane_b32 s68, v253, 4
	v_readlane_b32 s69, v253, 5
	v_readlane_b32 s70, v253, 6
	v_readlane_b32 s71, v253, 7
	v_readlane_b32 s65, v253, 1
	v_readlane_b32 s66, v253, 2
	v_readlane_b32 s67, v253, 3
	v_readlane_b32 s72, v253, 8
	v_readlane_b32 s73, v253, 9
	v_readlane_b32 s74, v253, 10
	v_readlane_b32 s75, v253, 11
	v_readlane_b32 s76, v253, 12
	v_readlane_b32 s77, v253, 13
	v_readlane_b32 s78, v253, 14
	v_readlane_b32 s79, v253, 15
	s_cbranch_scc1 .LBB0_682
	v_readlane_b32 s46, v253, 44
	v_readlane_b32 s47, v253, 45
	v_readlane_b32 s48, v253, 46
	v_readlane_b32 s49, v253, 47
	v_readfirstlane_b32 s4, v162
	s_nop 3
	s_lshr_b32 s4, s4, 6
	s_mov_b32 s29, 0x3e38aa3b
	v_mov_b32_e32 v238, 0xff800000
	v_and_b32_e32 v240, 15, v206
	v_lshrrev_b32_e32 v241, 4, v206
	v_and_b32_e32 v242, 7, v240
	v_xor_b32_e32 v242, v242, v241
	v_lshlrev_b32_e32 v242, 4, v242
	v_lshl_or_b32 v228, v240, 7, v242
	v_xor_b32_e32 v229, 64, v228
	v_add_u32_e32 v228, 49152, v228
	v_add_u32_e32 v229, 49152, v229
	v_and_b32_e32 v242, 1, v241
	v_lshrrev_b32_e32 v243, 1, v241
	v_lshlrev_b32_e32 v243, 8, v243
	v_lshl_or_b32 v243, v242, 10, v243
	v_lshrrev_b32_e32 v244, 2, v240
	v_lshl_or_b32 v243, v244, 6, v243
	v_and_b32_e32 v244, 3, v240
	v_lshl_or_b32 v243, v244, 3, v243
	v_lshlrev_b32_e32 v242, 5, v242
	v_or_b32_e32 v230, v243, v242
	v_xor_b32_e32 v242, 32, v242
	v_or_b32_e32 v231, v243, v242
	v_lshlrev_b32_e32 v242, 2, v241
	v_sub_u32_e32 v235, v240, v242
	v_lshlrev_b32_e32 v232, 2, v235
	v_add_u32_e32 v232, 98288, v232
	v_xor_b32_e32 v236, 16, v206
	v_lshlrev_b32_e32 v236, 2, v236
	v_xor_b32_e32 v237, 32, v206
	v_lshlrev_b32_e32 v237, 2, v237
	v_lshlrev_b32_e32 v242, 4, v241
	v_lshl_or_b32 v233, v240, 12, v242
	v_add_u32_e32 v196, 0x10000, v233
	v_lshlrev_b32_e32 v242, 3, v241
	v_lshl_or_b32 v234, v240, 12, v242
	v_add_u32_e32 v197, 0x10000, v234
	v_lshrrev_b32_e32 v240, 3, v162
	v_and_b32_e32 v241, 7, v162
	v_lshlrev_b32_e32 v242, 4, v241
	v_lshl_or_b32 v147, v240, 9, v242
	v_and_b32_e32 v242, 7, v240
	v_xor_b32_e32 v242, v242, v241
	v_lshlrev_b32_e32 v242, 4, v242
	v_lshl_or_b32 v148, v240, 7, v242
	v_add_u32_e32 v148, 49152, v148
	v_bfe_u32 v242, v240, 2, 1
	v_bfe_u32 v243, v240, 3, 1
	v_and_b32_e32 v244, 3, v240
	v_lshl_or_b32 v244, v243, 2, v244
	v_lshrrev_b32_e32 v245, 4, v240
	v_lshl_or_b32 v245, v245, 1, v242
	v_lshrrev_b32_e32 v246, 2, v241
	v_lshl_or_b32 v245, v245, 1, v246
	v_lshlrev_b32_e32 v245, 9, v245
	v_lshl_or_b32 v245, v244, 6, v245
	v_and_b32_e32 v246, 3, v241
	v_lshlrev_b32_e32 v246, 4, v246
	v_lshlrev_b32_e32 v242, 5, v242
	v_xor_b32_e32 v246, v246, v242
	v_or_b32_e32 v149, v245, v246
	s_getpc_b64 s[100:101]
	s_add_u32 s100, s100, _ZN3attL3T5BE@rel32@lo+4
	s_addc_u32 s101, s101, _ZN3attL3T5BE@rel32@hi+12
	v_mov_b32_e32 v150, 0
	v_cmp_gt_u32_e32 vcc, 0x80, v162
	s_nop 1
	s_and_saveexec_b64 s[0:1], vcc
	global_load_ubyte v150, v162, s[100:101]
	s_or_b64 exec, exec, s[0:1]
	v_lshlrev_b32_e32 v152, 2, v162
	v_add_u32_e32 v152, 98304, v152
	v_and_b32_e32 v153, 7, v206
	v_lshlrev_b32_e32 v153, 2, v153
	s_waitcnt vmcnt(0)
	v_lshlrev_b32_e32 v150, 7, v150
	s_and_b32 s5, s2, 63
	s_bfe_u32 s7, s2, 0x20006
	s_bfe_u32 s6, s2, 0x30008
	s_lshr_b32 s8, s2, 11
	s_lshl_b32 s9, s7, 3
	s_or_b32 s9, s9, s6
	s_lshl_b32 s13, s8, 14
	s_lshl_b32 s14, s5, 8
	s_add_u32 s13, s13, s14
	s_lshl_b32 s14, s4, 5
	s_add_u32 s13, s13, s14
	s_lshl_b32 s13, s13, 12
	s_lshl_b32 s14, s9, 7
	s_add_u32 s13, s13, s14
	s_add_u32 s64, s18, s13
	s_addc_u32 s65, s19, 0
	global_load_dwordx4 v[18:21], v233, s[64:65] offset:0
	global_load_dwordx4 v[22:25], v233, s[64:65] offset:64
	global_load_dwordx4 v[26:29], v196, s[64:65] offset:0
	global_load_dwordx4 v[30:33], v196, s[64:65] offset:64
	s_waitcnt vmcnt(0)
.Lsw_item:
	s_and_b32 s5, s2, 63
	s_bfe_u32 s7, s2, 0x20006
	s_bfe_u32 s6, s2, 0x30008
	s_lshr_b32 s8, s2, 11
	s_lshl_b32 s9, s7, 3
	s_or_b32 s9, s9, s6
	s_mov_b64 s[50:51], s[64:65]
	s_waitcnt vmcnt(8)
	v_mov_b32_e32 v2, v18
	v_mov_b32_e32 v3, v19
	v_mov_b32_e32 v4, v20
	v_mov_b32_e32 v5, v21
	v_mov_b32_e32 v6, v22
	v_mov_b32_e32 v7, v23
	v_mov_b32_e32 v8, v24
	v_mov_b32_e32 v9, v25
	v_mov_b32_e32 v10, v26
	v_mov_b32_e32 v11, v27
	v_mov_b32_e32 v12, v28
	v_mov_b32_e32 v13, v29
	v_mov_b32_e32 v14, v30
	v_mov_b32_e32 v15, v31
	v_mov_b32_e32 v16, v32
	v_mov_b32_e32 v17, v33
	s_cmp_lg_u32 s3, 0x100
	s_cselect_b32 s13, 0, s6
	s_cmp_lg_u32 s13, 0
	s_cbranch_scc1 .Lsw_staged
	s_waitcnt lgkmcnt(0)
	s_barrier
	s_cmp_eq_u32 s5, 0
	s_cselect_b32 s57, 4, 6
	s_cselect_b32 s14, 0, 0x80
	s_lshl_b32 s13, s8, 14
	s_lshl_b32 s15, s5, 8
	s_add_u32 s13, s13, s15
	s_sub_u32 s13, s13, s14
	s_lshl_b32 s13, s13, 9
	s_lshl_b32 s14, s7, 7
	s_add_u32 s13, s13, s14
	s_add_u32 s36, s46, s13
	s_addc_u32 s37, s47, 0
	s_add_u32 s38, s48, s13
	s_addc_u32 s39, s49, 0
	global_load_dwordx4 v[70:73], v147, s[36:37]
	global_load_dwordx4 v[74:77], v147, s[38:39]
	s_add_u32 s36, s36, 0x8000
	s_addc_u32 s37, s37, 0
	s_add_u32 s38, s38, 0x8000
	s_addc_u32 s39, s39, 0
	global_load_dwordx4 v[78:81], v147, s[36:37]
	global_load_dwordx4 v[82:85], v147, s[38:39]
	s_add_u32 s36, s36, 0x8000
	s_addc_u32 s37, s37, 0
	s_add_u32 s38, s38, 0x8000
	s_addc_u32 s39, s39, 0
	global_load_dwordx4 v[86:89], v147, s[36:37]
	global_load_dwordx4 v[90:93], v147, s[38:39]
	s_add_u32 s36, s36, 0x8000
	s_addc_u32 s37, s37, 0
	s_add_u32 s38, s38, 0x8000
	s_addc_u32 s39, s39, 0
	global_load_dwordx4 v[94:97], v147, s[36:37]
	global_load_dwordx4 v[98:101], v147, s[38:39]
	s_add_u32 s36, s36, 0x8000
	s_addc_u32 s37, s37, 0
	s_add_u32 s38, s38, 0x8000
	s_addc_u32 s39, s39, 0
	s_cmp_eq_u32 s57, 4
	s_cbranch_scc1 .Lsw_ld_done
	global_load_dwordx4 v[102:105], v147, s[36:37]
	global_load_dwordx4 v[106:109], v147, s[38:39]
	s_add_u32 s36, s36, 0x8000
	s_addc_u32 s37, s37, 0
	s_add_u32 s38, s38, 0x8000
	s_addc_u32 s39, s39, 0
	global_load_dwordx4 v[110:113], v147, s[36:37]
	global_load_dwordx4 v[114:117], v147, s[38:39]
; template <bool MLA> __device__ __forceinline__ void attn_unit(const AttnP& P, int b, int hh, int qb, LAS char* lds) {
;     ...
;         for (int d0 = 0; d0 < 4; ++d0) qr[d0] = *(const bf16x8*)(P.QS + qrow * 2048 + hh * 64 + d0 * 16 + hi * 8);
;         if (tid < 128) bias_l[tid] = P.rel[(int)T5B[tid] * 32 + hh] * (1.0f / SCALE);
;     }
;     bf16x8 sk0, sv0;
;     const int sr8 = tid >> 3, ch8 = tid & 7;
;     const bf16_t* Kg; const bf16_t* Vg; const bf16_t* Rg = nullptr;
;     unsigned okA = 0, okB = 0, orp = 0, ovA = 0, ovB = 0;
;     if constexpr (MLA) {
;         Kg = P.KN + rowbase * 2048 + hh * 128; Vg = P.V + rowbase * 2048 + hh * 128; Rg = P.KR + rowbase * 64;
;         { const int rA = 4 * wid + (lane >> 4), rB = rA + 32, cp = lane & 15; okA = (unsigned)(rA * 2048 + ((cp ^ (rA & 7)) << 3)); okB = (unsigned)(rB * 2048 + ((cp ^ (rB & 7)) << 3)); }
;         { const int rr = 8 * wid + (lane >> 3), cp = lane & 7; orp = (unsigned)(rr * 64 + ((cp ^ (rr & 7)) << 3)); }
;         { const int stA = 2 * wid + (lane >> 5), stB = stA + 16; const int kl = (lane & 31) >> 2, c8 = 8 * (lane & 3);
;           const int kkA = (stA >> 2) * 8 + kl, kkB = (stB >> 2) * 8 + kl;
;           const int kA = (kkA & ~0xC) | ((kkA & 4) << 1) | ((kkA & 8) >> 1), kB = (kkB & ~0xC) | ((kkB & 4) << 1) | ((kkB & 8) >> 1);
;           ovA = (unsigned)(kA * 2048 + 32 * (stA & 3) + c8); ovB = (unsigned)(kB * 2048 + 32 * (stB & 3) + c8); }
;     } else { Kg = P.KS + (rowbase + sr8) * 256 + (hh >> 3) * 64 + ch8 * 8; Vg = P.VS + (rowbase + sr8) * 256 + (hh >> 3) * 64 + ch8 * 8; }
;     const int kws = KSWZ64(sr8, ch8), vst0 = v_st<NCB>(sr8, ch8 * 8);
;     ...
;     float m_reg = MLA ? 0.f : P.sinks[hh] * (1.0f / SCALE), l_reg = MLA ? 0.f : 1.f;
;     f32x16 o[NCB];
; #pragma unroll
;     for (int d = 0; d < NCB; ++d) o[d] = f32x16{};
;     const int vb0 = (int)(uintptr_t)V_lds + v_rd_base(lane);
;     LOADT(0, 0); asm volatile("s_waitcnt vmcnt(0)" ::: "memory"); WRITET(0); __syncthreads();
;     for (int t = 0; t < NT; ++t) {
;         const int buf = t & 1;
;         if (t + 1 < NT) LOADT(t + 1, buf ^ 1);
;         const int kb = kbase0 + 64 * t;
;         const bool act = (kb <= qlo + 31) && (MLA || kb + 63 >= qlo - (W - 1));
;         if (act) {
;             f32x16 p0 = f32x16{}, p1 = f32x16{};
;             if constexpr (MLA) {
; #pragma unroll
.Lsw_ld_done:
	s_lshl_b32 s13, s7, 5
	v_add_u32_e32 v240, s13, v150
	v_add_u32_e32 v241, s13, v153
	v_cmp_gt_u32_e32 vcc, 0x80, v162
	s_nop 1
	s_and_saveexec_b64 s[0:1], vcc
	global_load_dwordx4 v[118:121], v240, s[70:71]
	global_load_dwordx4 v[122:125], v240, s[70:71] offset:16
	s_or_b64 exec, exec, s[0:1]
	global_load_dword v151, v241, s[68:69]
	s_waitcnt vmcnt(0)
	ds_write_b128 v148, v[70:73] offset:0
	ds_write_b128 v149, v[74:77] offset:0
	ds_write_b128 v148, v[78:81] offset:8192
	ds_write_b128 v149, v[82:85] offset:8192
	ds_write_b128 v148, v[86:89] offset:16384
	ds_write_b128 v149, v[90:93] offset:16384
	ds_write_b128 v148, v[94:97] offset:24576
	ds_write_b128 v149, v[98:101] offset:24576
	s_cmp_eq_u32 s57, 4
	s_cbranch_scc1 .Lsw_wr_done
	ds_write_b128 v148, v[102:105] offset:32768
	ds_write_b128 v149, v[106:109] offset:32768
	ds_write_b128 v148, v[110:113] offset:40960
	ds_write_b128 v149, v[114:117] offset:40960
.Lsw_wr_done:
	v_mul_f32_e32 v151, 0x41000000, v151
	v_cmp_gt_u32_e32 vcc, 0x80, v162
	s_nop 1
	s_and_saveexec_b64 s[0:1], vcc
	v_mul_f32_e32 v118, 0x41000000, v118
	v_mul_f32_e32 v119, 0x41000000, v119
	v_mul_f32_e32 v120, 0x41000000, v120
	v_mul_f32_e32 v121, 0x41000000, v121
	v_mul_f32_e32 v122, 0x41000000, v122
	v_mul_f32_e32 v123, 0x41000000, v123
	v_mul_f32_e32 v124, 0x41000000, v124
	v_mul_f32_e32 v125, 0x41000000, v125
	ds_write_b32 v152, v118 offset:0
	ds_write_b32 v152, v119 offset:512
	ds_write_b32 v152, v120 offset:1024
	ds_write_b32 v152, v121 offset:1536
	ds_write_b32 v152, v122 offset:2048
	ds_write_b32 v152, v123 offset:2560
	ds_write_b32 v152, v124 offset:3072
	ds_write_b32 v152, v125 offset:3584
	s_or_b64 exec, exec, s[0:1]
	s_waitcnt lgkmcnt(0)
	s_barrier
.Lsw_staged:
	s_add_u32 s40, s2, s3
	s_cmp_lt_u32 s40, 0x1000
	s_cbranch_scc0 .Lsw_nopf
	s_and_b32 s98, s40, 63
	s_bfe_u32 s100, s40, 0x20006
	s_bfe_u32 s99, s40, 0x30008
	s_lshr_b32 s101, s40, 11
	s_lshl_b32 s15, s100, 3
	s_or_b32 s15, s15, s99
	s_lshl_b32 s13, s101, 14
	s_lshl_b32 s14, s98, 8
	s_add_u32 s13, s13, s14
	s_lshl_b32 s14, s4, 5
	s_add_u32 s13, s13, s14
	s_lshl_b32 s13, s13, 12
	s_lshl_b32 s14, s15, 7
	s_add_u32 s13, s13, s14
	s_add_u32 s64, s18, s13
	s_addc_u32 s65, s19, 0
	global_load_dwordx4 v[18:21], v233, s[64:65] offset:0
	global_load_dwordx4 v[22:25], v233, s[64:65] offset:64
	global_load_dwordx4 v[26:29], v196, s[64:65] offset:0
	global_load_dwordx4 v[30:33], v196, s[64:65] offset:64
.Lsw_nopf:
	s_nop 3
	v_readlane_b32 s28, v151, s6
	s_lshl_b32 s33, s6, 9
	v_add_u32_e32 v146, s33, v232
	s_lshl_b32 s16, s4, 1
	s_cmp_eq_u32 s5, 0
	s_cselect_b32 s13, 8, 0
	s_sub_i32 s16, s16, s13
	ds_read_b32 v34, v146 offset:528
	ds_read_b32 v35, v146 offset:524
	ds_read_b32 v36, v146 offset:520
	ds_read_b32 v37, v146 offset:516
	ds_read_b32 v38, v146 offset:464
	ds_read_b32 v39, v146 offset:460
	ds_read_b32 v40, v146 offset:456
	ds_read_b32 v41, v146 offset:452
	ds_read_b32 v42, v146 offset:400
	ds_read_b32 v43, v146 offset:396
	ds_read_b32 v44, v146 offset:392
	ds_read_b32 v45, v146 offset:388
	ds_read_b32 v46, v146 offset:336
	ds_read_b32 v47, v146 offset:332
	ds_read_b32 v48, v146 offset:328
	ds_read_b32 v49, v146 offset:324
	ds_read_b32 v50, v146 offset:272
	ds_read_b32 v51, v146 offset:268
	ds_read_b32 v52, v146 offset:264
	ds_read_b32 v53, v146 offset:260
	ds_read_b32 v54, v146 offset:208
	ds_read_b32 v55, v146 offset:204
	ds_read_b32 v56, v146 offset:200
	ds_read_b32 v57, v146 offset:196
	ds_read_b32 v58, v146 offset:144
	ds_read_b32 v59, v146 offset:140
	ds_read_b32 v60, v146 offset:136
	ds_read_b32 v61, v146 offset:132
	ds_read_b32 v62, v146 offset:80
	ds_read_b32 v63, v146 offset:76
	ds_read_b32 v64, v146 offset:72
	ds_read_b32 v65, v146 offset:68
	ds_read_b32 v66, v146 offset:16
	ds_read_b32 v67, v146 offset:12
	ds_read_b32 v68, v146 offset:8
	ds_read_b32 v69, v146 offset:4
	v_mov_b32_e32 v164, 0
	v_mov_b32_e32 v165, 0
	v_mov_b32_e32 v166, 0
	v_mov_b32_e32 v167, 0
	v_mov_b32_e32 v168, 0
	v_mov_b32_e32 v169, 0
	v_mov_b32_e32 v170, 0
	v_mov_b32_e32 v171, 0
	v_mov_b32_e32 v172, 0
	v_mov_b32_e32 v173, 0
	v_mov_b32_e32 v174, 0
	v_mov_b32_e32 v175, 0
	v_mov_b32_e32 v176, 0
	v_mov_b32_e32 v177, 0
	v_mov_b32_e32 v178, 0
	v_mov_b32_e32 v179, 0
	v_mov_b32_e32 v180, 0
	v_mov_b32_e32 v181, 0
	v_mov_b32_e32 v182, 0
	v_mov_b32_e32 v183, 0
	v_mov_b32_e32 v184, 0
	v_mov_b32_e32 v185, 0
	v_mov_b32_e32 v186, 0
	v_mov_b32_e32 v187, 0
	v_mov_b32_e32 v188, 0
	v_mov_b32_e32 v189, 0
	v_mov_b32_e32 v190, 0
	v_mov_b32_e32 v191, 0
	v_mov_b32_e32 v192, 0
	v_mov_b32_e32 v193, 0
	v_mov_b32_e32 v194, 0
	v_mov_b32_e32 v195, 0
	v_mov_b32_e32 v224, 0
	v_mov_b32_e32 v225, 0
	v_mov_b32_e32 v226, 0
	v_mov_b32_e32 v227, 0
	s_waitcnt lgkmcnt(0)
	v_cmp_gt_i32_e32 vcc, 0, v235
	s_nop 1
	v_cndmask_b32_e32 v34, v238, v34, vcc
	v_cndmask_b32_e32 v66, v66, v238, vcc
	v_cmp_gt_i32_e32 vcc, 1, v235
	s_nop 1
	v_cndmask_b32_e32 v35, v238, v35, vcc
	v_cndmask_b32_e32 v67, v67, v238, vcc
	v_cmp_gt_i32_e32 vcc, 2, v235
	s_nop 1
	v_cndmask_b32_e32 v36, v238, v36, vcc
	v_cndmask_b32_e32 v68, v68, v238, vcc
	v_cmp_gt_i32_e32 vcc, 3, v235
	s_nop 1
	v_cndmask_b32_e32 v37, v238, v37, vcc
	v_cndmask_b32_e32 v69, v69, v238, vcc
	s_add_i32 s17, s16, 0
	s_max_i32 s17, s17, 0
	s_lshl_b32 s17, s17, 11
	v_add_u32_e32 v142, s17, v228
	v_add_u32_e32 v143, s17, v229
	ds_read_b128 v[208:211], v142 offset:0
	ds_read_b128 v[212:215], v143 offset:0
	ds_read_b128 v[216:219], v142 offset:2048
	ds_read_b128 v[220:223], v143 offset:2048
	s_waitcnt lgkmcnt(3)
	v_mfma_f32_16x16x32_bf16 v[70:73], v[208:211], v[2:5], v[34:37]
	s_add_i32 s17, s16, 2
	s_max_i32 s17, s17, 0
	s_lshl_b32 s17, s17, 11
	v_add_u32_e32 v144, s17, v228
	v_add_u32_e32 v145, s17, v229
	ds_read_b128 v[208:211], v144 offset:0
	s_waitcnt lgkmcnt(3)
; #define LAS __attribute__((address_space(3)))
; __device__ __forceinline__ void qk64(f32x16& p0, f32x16& p1, const LAS char* kl, int r32, int hi, const bf16x8* qr) {
; #pragma unroll
;     for (int ks = 0; ks < 4; ++ks) { const LAS char* a = kl + KSWZ64(r32, 2 * ks + hi);
;         const bf16x8 b0 = *reinterpret_cast<const LAS bf16x8*>(a);
;         const bf16x8 b1 = *reinterpret_cast<const LAS bf16x8*>(a + 32 * 128);
;         p0 = __builtin_amdgcn_mfma_f32_32x32x16_bf16(b0, qr[ks], p0, 0, 0, 0);
;         p1 = __builtin_amdgcn_mfma_f32_32x32x16_bf16(b1, qr[ks], p1, 0, 0, 0); }
; }
; template <bool MLA> __device__ __forceinline__ void attn_unit(const AttnP& P, int b, int hh, int qb, LAS char* lds) {
;     ...
;             else { qk64(p0, p1, K_lds + buf * KBYTES, r32, hi, qr); }
;             const int dq = qm - kb;
;             if constexpr (!MLA) {
; #pragma unroll
;                 for (int r = 0; r < 16; ++r) { const int c = (r & 3) + 8 * (r >> 2); p0[r] += bias_l[(dq - c) & 127]; p1[r] += bias_l[(dq - c - 32) & 127]; }
;             }
;             if (kb + 63 > qlo || (!MLA && kb <= qlo + 31 - W)) mask_tile(p0, p1, dq, (unsigned)W);
	v_mfma_f32_16x16x32_bf16 v[70:73], v[212:215], v[6:9], v[70:73]
	ds_read_b128 v[212:215], v145 offset:0
	s_waitcnt lgkmcnt(3)
	v_mfma_f32_16x16x32_bf16 v[74:77], v[216:219], v[2:5], v[38:41]
	v_mfma_f32_16x16x32_bf16 v[106:109], v[216:219], v[10:13], v[34:37]
	ds_read_b128 v[216:219], v144 offset:2048
	s_waitcnt lgkmcnt(3)
	v_mfma_f32_16x16x32_bf16 v[74:77], v[220:223], v[6:9], v[74:77]
	v_mfma_f32_16x16x32_bf16 v[106:109], v[220:223], v[14:17], v[106:109]
	ds_read_b128 v[220:223], v145 offset:2048
	s_waitcnt lgkmcnt(3)
	v_mfma_f32_16x16x32_bf16 v[78:81], v[208:211], v[2:5], v[42:45]
	v_mfma_f32_16x16x32_bf16 v[110:113], v[208:211], v[10:13], v[38:41]
	s_add_i32 s17, s16, 4
	s_max_i32 s17, s17, 0
	s_lshl_b32 s17, s17, 11
	v_add_u32_e32 v158, s17, v228
	v_add_u32_e32 v159, s17, v229
	ds_read_b128 v[208:211], v158 offset:0
	s_waitcnt lgkmcnt(3)
	v_mfma_f32_16x16x32_bf16 v[78:81], v[212:215], v[6:9], v[78:81]
	v_mfma_f32_16x16x32_bf16 v[110:113], v[212:215], v[14:17], v[110:113]
	ds_read_b128 v[212:215], v159 offset:0
	s_waitcnt lgkmcnt(3)
	v_mfma_f32_16x16x32_bf16 v[82:85], v[216:219], v[2:5], v[46:49]
	v_mfma_f32_16x16x32_bf16 v[114:117], v[216:219], v[10:13], v[42:45]
	ds_read_b128 v[216:219], v158 offset:2048
	s_waitcnt lgkmcnt(3)
	v_mfma_f32_16x16x32_bf16 v[82:85], v[220:223], v[6:9], v[82:85]
	v_mfma_f32_16x16x32_bf16 v[114:117], v[220:223], v[14:17], v[114:117]
	ds_read_b128 v[220:223], v159 offset:2048
	s_waitcnt lgkmcnt(3)
	v_mfma_f32_16x16x32_bf16 v[86:89], v[208:211], v[2:5], v[50:53]
	v_mfma_f32_16x16x32_bf16 v[118:121], v[208:211], v[10:13], v[46:49]
	s_add_i32 s17, s16, 6
	s_max_i32 s17, s17, 0
	s_lshl_b32 s17, s17, 11
	v_add_u32_e32 v160, s17, v228
	v_add_u32_e32 v161, s17, v229
	ds_read_b128 v[208:211], v160 offset:0
	s_waitcnt lgkmcnt(3)
	v_mfma_f32_16x16x32_bf16 v[86:89], v[212:215], v[6:9], v[86:89]
	v_mfma_f32_16x16x32_bf16 v[118:121], v[212:215], v[14:17], v[118:121]
	ds_read_b128 v[212:215], v161 offset:0
	s_waitcnt lgkmcnt(3)
	v_mfma_f32_16x16x32_bf16 v[90:93], v[216:219], v[2:5], v[54:57]
	v_mfma_f32_16x16x32_bf16 v[122:125], v[216:219], v[10:13], v[50:53]
	ds_read_b128 v[216:219], v160 offset:2048
	s_waitcnt lgkmcnt(3)
	v_mfma_f32_16x16x32_bf16 v[90:93], v[220:223], v[6:9], v[90:93]
	v_mfma_f32_16x16x32_bf16 v[122:125], v[220:223], v[14:17], v[122:125]
	ds_read_b128 v[220:223], v161 offset:2048
	s_waitcnt lgkmcnt(3)
	v_mfma_f32_16x16x32_bf16 v[94:97], v[208:211], v[2:5], v[58:61]
	v_mfma_f32_16x16x32_bf16 v[126:129], v[208:211], v[10:13], v[54:57]
	s_add_i32 s17, s16, 8
	s_max_i32 s17, s17, 0
	s_lshl_b32 s17, s17, 11
	v_add_u32_e32 v204, s17, v228
	v_add_u32_e32 v207, s17, v229
	ds_read_b128 v[208:211], v204 offset:0
	s_waitcnt lgkmcnt(3)
	v_mfma_f32_16x16x32_bf16 v[94:97], v[212:215], v[6:9], v[94:97]
	v_mfma_f32_16x16x32_bf16 v[126:129], v[212:215], v[14:17], v[126:129]
	ds_read_b128 v[212:215], v207 offset:0
	s_waitcnt lgkmcnt(3)
	v_mfma_f32_16x16x32_bf16 v[98:101], v[216:219], v[2:5], v[62:65]
	v_mfma_f32_16x16x32_bf16 v[130:133], v[216:219], v[10:13], v[58:61]
	ds_read_b128 v[216:219], v204 offset:2048
	s_waitcnt lgkmcnt(3)
	v_mfma_f32_16x16x32_bf16 v[98:101], v[220:223], v[6:9], v[98:101]
	v_mfma_f32_16x16x32_bf16 v[130:133], v[220:223], v[14:17], v[130:133]
	ds_read_b128 v[220:223], v207 offset:2048
	s_waitcnt lgkmcnt(3)
	v_mfma_f32_16x16x32_bf16 v[102:105], v[208:211], v[2:5], v[66:69]
	v_mfma_f32_16x16x32_bf16 v[134:137], v[208:211], v[10:13], v[62:65]
	s_waitcnt lgkmcnt(2)
	v_mfma_f32_16x16x32_bf16 v[102:105], v[212:215], v[6:9], v[102:105]
	v_mfma_f32_16x16x32_bf16 v[134:137], v[212:215], v[14:17], v[134:137]
	s_waitcnt lgkmcnt(1)
	v_mfma_f32_16x16x32_bf16 v[138:141], v[216:219], v[10:13], v[66:69]
	s_waitcnt lgkmcnt(0)
	v_mfma_f32_16x16x32_bf16 v[138:141], v[220:223], v[14:17], v[138:141]
	s_nop 7
	s_cmp_lt_i32 s16, 0
	s_cbranch_scc0 .Lsw_nofirst
	s_add_i32 s13, s16, 0
	s_cmp_lt_i32 s13, 0
	s_cbranch_scc0 .Lsw_nf_0_0
	v_mov_b32_e32 v70, v238
	v_mov_b32_e32 v71, v238
	v_mov_b32_e32 v72, v238
	v_mov_b32_e32 v73, v238
.Lsw_nf_0_0:
	s_add_i32 s13, s16, 1
	s_cmp_lt_i32 s13, 0
	s_cbranch_scc0 .Lsw_nf_0_1
	v_mov_b32_e32 v74, v238
	v_mov_b32_e32 v75, v238
	v_mov_b32_e32 v76, v238
	v_mov_b32_e32 v77, v238
.Lsw_nf_0_1:
	s_add_i32 s13, s16, 2
	s_cmp_lt_i32 s13, 0
	s_cbranch_scc0 .Lsw_nf_0_2
	v_mov_b32_e32 v78, v238
	v_mov_b32_e32 v79, v238
	v_mov_b32_e32 v80, v238
	v_mov_b32_e32 v81, v238
.Lsw_nf_0_2:
	s_add_i32 s13, s16, 3
	s_cmp_lt_i32 s13, 0
	s_cbranch_scc0 .Lsw_nf_0_3
	v_mov_b32_e32 v82, v238
	v_mov_b32_e32 v83, v238
	v_mov_b32_e32 v84, v238
	v_mov_b32_e32 v85, v238
.Lsw_nf_0_3:
	s_add_i32 s13, s16, 4
	s_cmp_lt_i32 s13, 0
	s_cbranch_scc0 .Lsw_nf_0_4
	v_mov_b32_e32 v86, v238
	v_mov_b32_e32 v87, v238
	v_mov_b32_e32 v88, v238
	v_mov_b32_e32 v89, v238
.Lsw_nf_0_4:
	s_add_i32 s13, s16, 5
	s_cmp_lt_i32 s13, 0
	s_cbranch_scc0 .Lsw_nf_0_5
	v_mov_b32_e32 v90, v238
	v_mov_b32_e32 v91, v238
	v_mov_b32_e32 v92, v238
	v_mov_b32_e32 v93, v238
.Lsw_nf_0_5:
	s_add_i32 s13, s16, 6
	s_cmp_lt_i32 s13, 0
	s_cbranch_scc0 .Lsw_nf_0_6
	v_mov_b32_e32 v94, v238
	v_mov_b32_e32 v95, v238
	v_mov_b32_e32 v96, v238
	v_mov_b32_e32 v97, v238
.Lsw_nf_0_6:
	s_add_i32 s13, s16, 7
	s_cmp_lt_i32 s13, 0
	s_cbranch_scc0 .Lsw_nf_0_7
	v_mov_b32_e32 v98, v238
	v_mov_b32_e32 v99, v238
	v_mov_b32_e32 v100, v238
	v_mov_b32_e32 v101, v238
.Lsw_nf_0_7:
	s_add_i32 s13, s16, 8
	s_cmp_lt_i32 s13, 0
	s_cbranch_scc0 .Lsw_nf_0_8
	v_mov_b32_e32 v102, v238
	v_mov_b32_e32 v103, v238
	v_mov_b32_e32 v104, v238
	v_mov_b32_e32 v105, v238
.Lsw_nf_0_8:
	s_add_i32 s13, s16, 1
	s_cmp_lt_i32 s13, 0
	s_cbranch_scc0 .Lsw_nf_1_0
	v_mov_b32_e32 v106, v238
	v_mov_b32_e32 v107, v238
	v_mov_b32_e32 v108, v238
	v_mov_b32_e32 v109, v238
; template <int SCALE_E6> __device__ __forceinline__ void partialSM(f32x16& p0, f32x16& p1, float& m_reg, float& mn, float& alpha) {
;     constexpr float SCALE = SCALE_E6 * 1e-9f; constexpr float C2 = 1.4426950408889634f * SCALE;
;     float pmax = p0[0];
; #pragma unroll
;     for (int r = 1; r < 16; ++r) pmax = fmaxf(pmax, p0[r]);
; #pragma unroll
;     for (int r = 0; r < 16; ++r) pmax = fmaxf(pmax, p1[r]);
;     { auto rr = __builtin_amdgcn_permlane32_swap(__float_as_uint(pmax), __float_as_uint(pmax), false, false);
;       pmax = fmaxf(__uint_as_float(rr[0]), __uint_as_float(rr[1])); }
;     if (__builtin_expect(__all((pmax - m_reg) * SCALE <= THR), 1)) { mn = m_reg; alpha = 1.f; }
;     else { mn = fmaxf(m_reg, pmax); alpha = __builtin_amdgcn_exp2f((m_reg - mn) * C2); m_reg = mn; }
;     const float mnL = -mn * C2;
; #pragma unroll
;     for (int r = 0; r < 16; ++r) p0[r] = fmaf(p0[r], C2, mnL);
; #pragma unroll
;     for (int r = 0; r < 16; ++r) p1[r] = fmaf(p1[r], C2, mnL);
; #pragma unroll
;     for (int r = 0; r < 16; ++r) p0[r] = __builtin_amdgcn_exp2f(p0[r]);
.Lsw_nf_1_0:
	s_add_i32 s13, s16, 2
	s_cmp_lt_i32 s13, 0
	s_cbranch_scc0 .Lsw_nf_1_1
	v_mov_b32_e32 v110, v238
	v_mov_b32_e32 v111, v238
	v_mov_b32_e32 v112, v238
	v_mov_b32_e32 v113, v238
.Lsw_nf_1_1:
	s_add_i32 s13, s16, 3
	s_cmp_lt_i32 s13, 0
	s_cbranch_scc0 .Lsw_nf_1_2
	v_mov_b32_e32 v114, v238
	v_mov_b32_e32 v115, v238
	v_mov_b32_e32 v116, v238
	v_mov_b32_e32 v117, v238
.Lsw_nf_1_2:
	s_add_i32 s13, s16, 4
	s_cmp_lt_i32 s13, 0
	s_cbranch_scc0 .Lsw_nf_1_3
	v_mov_b32_e32 v118, v238
	v_mov_b32_e32 v119, v238
	v_mov_b32_e32 v120, v238
	v_mov_b32_e32 v121, v238
.Lsw_nf_1_3:
	s_add_i32 s13, s16, 5
	s_cmp_lt_i32 s13, 0
	s_cbranch_scc0 .Lsw_nf_1_4
	v_mov_b32_e32 v122, v238
	v_mov_b32_e32 v123, v238
	v_mov_b32_e32 v124, v238
	v_mov_b32_e32 v125, v238
.Lsw_nf_1_4:
	s_add_i32 s13, s16, 6
	s_cmp_lt_i32 s13, 0
	s_cbranch_scc0 .Lsw_nf_1_5
	v_mov_b32_e32 v126, v238
	v_mov_b32_e32 v127, v238
	v_mov_b32_e32 v128, v238
	v_mov_b32_e32 v129, v238
.Lsw_nf_1_5:
	s_add_i32 s13, s16, 7
	s_cmp_lt_i32 s13, 0
	s_cbranch_scc0 .Lsw_nf_1_6
	v_mov_b32_e32 v130, v238
	v_mov_b32_e32 v131, v238
	v_mov_b32_e32 v132, v238
	v_mov_b32_e32 v133, v238
.Lsw_nf_1_6:
	s_add_i32 s13, s16, 8
	s_cmp_lt_i32 s13, 0
	s_cbranch_scc0 .Lsw_nf_1_7
	v_mov_b32_e32 v134, v238
	v_mov_b32_e32 v135, v238
	v_mov_b32_e32 v136, v238
	v_mov_b32_e32 v137, v238
.Lsw_nf_1_7:
	s_add_i32 s13, s16, 9
	s_cmp_lt_i32 s13, 0
	s_cbranch_scc0 .Lsw_nf_1_8
	v_mov_b32_e32 v138, v238
	v_mov_b32_e32 v139, v238
	v_mov_b32_e32 v140, v238
	v_mov_b32_e32 v141, v238
.Lsw_nf_1_8:
.Lsw_nofirst:
	v_max3_f32 v154, v70, v71, v72
	v_max3_f32 v154, v154, v73, v74
	v_max3_f32 v154, v154, v75, v76
	v_max3_f32 v154, v154, v77, v78
	v_max3_f32 v154, v154, v79, v80
	v_max3_f32 v154, v154, v81, v82
	v_max3_f32 v154, v154, v83, v84
	v_max3_f32 v154, v154, v85, v86
	v_max3_f32 v154, v154, v87, v88
	v_max3_f32 v154, v154, v89, v90
	v_max3_f32 v154, v154, v91, v92
	v_max3_f32 v154, v154, v93, v94
	v_max3_f32 v154, v154, v95, v96
	v_max3_f32 v154, v154, v97, v98
	v_max3_f32 v154, v154, v99, v100
	v_max3_f32 v154, v154, v101, v102
	v_max3_f32 v154, v154, v103, v104
	v_max_f32_e32 v154, v154, v105
	v_max3_f32 v155, v106, v107, v108
	v_max3_f32 v155, v155, v109, v110
	v_max3_f32 v155, v155, v111, v112
	v_max3_f32 v155, v155, v113, v114
	v_max3_f32 v155, v155, v115, v116
	v_max3_f32 v155, v155, v117, v118
	v_max3_f32 v155, v155, v119, v120
	v_max3_f32 v155, v155, v121, v122
	v_max3_f32 v155, v155, v123, v124
	v_max3_f32 v155, v155, v125, v126
	v_max3_f32 v155, v155, v127, v128
	v_max3_f32 v155, v155, v129, v130
	v_max3_f32 v155, v155, v131, v132
	v_max3_f32 v155, v155, v133, v134
	v_max3_f32 v155, v155, v135, v136
	v_max3_f32 v155, v155, v137, v138
	v_max3_f32 v155, v155, v139, v140
	v_max_f32_e32 v155, v155, v141
	ds_bpermute_b32 v240, v236, v154
	ds_bpermute_b32 v241, v236, v155
	s_waitcnt lgkmcnt(0)
	v_max_f32_e32 v154, v154, v240
	v_max_f32_e32 v155, v155, v241
	ds_bpermute_b32 v240, v237, v154
	ds_bpermute_b32 v241, v237, v155
	s_waitcnt lgkmcnt(0)
	v_max_f32_e32 v154, v154, v240
	v_max_f32_e32 v155, v155, v241
	v_max_f32_e32 v154, s28, v154
	v_mul_f32_e64 v156, -v154, s29
	v_max_f32_e32 v155, s28, v155
	v_mul_f32_e64 v157, -v155, s29
	v_fma_f32 v70, v70, s29, v156
	v_fma_f32 v71, v71, s29, v156
	v_fma_f32 v72, v72, s29, v156
	v_fma_f32 v73, v73, s29, v156
	v_fma_f32 v74, v74, s29, v156
	v_fma_f32 v75, v75, s29, v156
	v_fma_f32 v76, v76, s29, v156
	v_fma_f32 v77, v77, s29, v156
	v_fma_f32 v78, v78, s29, v156
	v_fma_f32 v79, v79, s29, v156
	v_fma_f32 v80, v80, s29, v156
	v_fma_f32 v81, v81, s29, v156
	v_fma_f32 v82, v82, s29, v156
	v_fma_f32 v83, v83, s29, v156
	v_fma_f32 v84, v84, s29, v156
	v_fma_f32 v85, v85, s29, v156
	v_fma_f32 v86, v86, s29, v156
	v_fma_f32 v87, v87, s29, v156
	v_fma_f32 v88, v88, s29, v156
	v_fma_f32 v89, v89, s29, v156
	v_fma_f32 v90, v90, s29, v156
	v_fma_f32 v91, v91, s29, v156
	v_fma_f32 v92, v92, s29, v156
	v_fma_f32 v93, v93, s29, v156
	v_fma_f32 v94, v94, s29, v156
	v_fma_f32 v95, v95, s29, v156
	v_fma_f32 v96, v96, s29, v156
	v_fma_f32 v97, v97, s29, v156
	v_fma_f32 v98, v98, s29, v156
	v_fma_f32 v99, v99, s29, v156
	v_fma_f32 v100, v100, s29, v156
	v_fma_f32 v101, v101, s29, v156
	v_fma_f32 v102, v102, s29, v156
	v_fma_f32 v103, v103, s29, v156
	v_fma_f32 v104, v104, s29, v156
	v_fma_f32 v105, v105, s29, v156
	v_fma_f32 v106, v106, s29, v157
	v_fma_f32 v107, v107, s29, v157
	v_fma_f32 v108, v108, s29, v157
	v_fma_f32 v109, v109, s29, v157
	v_fma_f32 v110, v110, s29, v157
	v_fma_f32 v111, v111, s29, v157
	v_fma_f32 v112, v112, s29, v157
	v_fma_f32 v113, v113, s29, v157
	v_fma_f32 v114, v114, s29, v157
	v_fma_f32 v115, v115, s29, v157
	v_fma_f32 v116, v116, s29, v157
	v_fma_f32 v117, v117, s29, v157
	v_fma_f32 v118, v118, s29, v157
	v_fma_f32 v119, v119, s29, v157
	v_fma_f32 v120, v120, s29, v157
	v_fma_f32 v121, v121, s29, v157
	v_fma_f32 v122, v122, s29, v157
	v_fma_f32 v123, v123, s29, v157
	v_fma_f32 v124, v124, s29, v157
	v_fma_f32 v125, v125, s29, v157
	v_fma_f32 v126, v126, s29, v157
	v_fma_f32 v127, v127, s29, v157
	v_fma_f32 v128, v128, s29, v157
	v_fma_f32 v129, v129, s29, v157
	v_fma_f32 v130, v130, s29, v157
	v_fma_f32 v131, v131, s29, v157
	v_fma_f32 v132, v132, s29, v157
	v_fma_f32 v133, v133, s29, v157
	v_fma_f32 v134, v134, s29, v157
	v_fma_f32 v135, v135, s29, v157
	v_fma_f32 v136, v136, s29, v157
	v_fma_f32 v137, v137, s29, v157
	v_fma_f32 v138, v138, s29, v157
	v_fma_f32 v139, v139, s29, v157
	v_fma_f32 v140, v140, s29, v157
	v_fma_f32 v141, v141, s29, v157
	v_exp_f32_e32 v70, v70
	v_exp_f32_e32 v71, v71
	v_exp_f32_e32 v72, v72
	v_exp_f32_e32 v73, v73
	v_exp_f32_e32 v74, v74
; #define PV_RD(S, d0) do { constexpr int b_ = (d0) * 512; TRRD(S##l0, b_); TRRD(S##h0, b_ + KS_ / 2); TRRD(S##l1, b_ + KS_); TRRD(S##h1, b_ + KS_ + KS_ / 2); TRRD(S##l2, b_ + 2 * KS_); TRRD(S##h2, b_ + 2 * KS_ + KS_ / 2); TRRD(S##l3, b_ + 3 * KS_); TRRD(S##h3, b_ + 3 * KS_ + KS_ / 2); } while (0)
; #define WL(n) do { asm volatile("s_waitcnt lgkmcnt(" #n ")" ::: "memory"); SBAR(); } while (0)
; __device__ __forceinline__ void finishSM(f32x16& p0, f32x16& p1, float alpha, float& l_reg, bf16x8& pa0, bf16x8& pa1, bf16x8& pa2, bf16x8& pa3) {
; #pragma unroll
;     for (int r = 0; r < 16; ++r) p1[r] = __builtin_amdgcn_exp2f(p1[r]);
;     float ps = 0;
; #pragma unroll
;     for (int r = 0; r < 16; ++r) ps += p0[r];
; #pragma unroll
;     for (int r = 0; r < 16; ++r) ps += p1[r];
;     { auto rr = __builtin_amdgcn_permlane32_swap(__float_as_uint(ps), __float_as_uint(ps), false, false);
;       ps = __uint_as_float(rr[0]) + __uint_as_float(rr[1]); }
;     l_reg = l_reg * alpha + ps;
;     ...
;     PK4(p0, 0, pa0); PK4(p0, 8, pa1); PK4(p1, 0, pa2); PK4(p1, 8, pa3);
; template <int NCB> __device__ __forceinline__ void pv_tile(f32x16* o, int vb, bf16x8 pa0, bf16x8 pa1, bf16x8 pa2, bf16x8 pa3) {
;     ...
;     constexpr int KS_ = NCB * 1024;
;     ...
;     s16x4 Al0, Al1, Al2, Al3, Ah0, Ah1, Ah2, Ah3, Bl0, Bl1, Bl2, Bl3, Bh0, Bh1, Bh2, Bh3;
;     PV_RD(A, 0); PV_RD(B, 1); WL(8); PV_MM(A, 0);
;     if constexpr (NCB == 4) { PV_RD(A, 2); WL(8); PV_MM(B, 1); PV_RD(B, 3); WL(8); PV_MM(A, 2); WL(0); PV_MM(B, 3); }
	v_exp_f32_e32 v75, v75
	v_exp_f32_e32 v76, v76
	v_exp_f32_e32 v77, v77
	v_exp_f32_e32 v78, v78
	v_exp_f32_e32 v79, v79
	v_exp_f32_e32 v80, v80
	v_exp_f32_e32 v81, v81
	v_exp_f32_e32 v82, v82
	v_exp_f32_e32 v83, v83
	v_exp_f32_e32 v84, v84
	v_exp_f32_e32 v85, v85
	v_exp_f32_e32 v86, v86
	v_exp_f32_e32 v87, v87
	v_exp_f32_e32 v88, v88
	v_exp_f32_e32 v89, v89
	v_exp_f32_e32 v90, v90
	v_exp_f32_e32 v91, v91
	v_exp_f32_e32 v92, v92
	v_exp_f32_e32 v93, v93
	v_exp_f32_e32 v94, v94
	v_exp_f32_e32 v95, v95
	v_exp_f32_e32 v96, v96
	v_exp_f32_e32 v97, v97
	v_exp_f32_e32 v98, v98
	v_exp_f32_e32 v99, v99
	v_exp_f32_e32 v100, v100
	v_exp_f32_e32 v101, v101
	v_exp_f32_e32 v102, v102
	v_exp_f32_e32 v103, v103
	v_exp_f32_e32 v104, v104
	v_exp_f32_e32 v105, v105
	v_exp_f32_e32 v106, v106
	v_exp_f32_e32 v107, v107
	v_exp_f32_e32 v108, v108
	v_exp_f32_e32 v109, v109
	v_exp_f32_e32 v110, v110
	v_exp_f32_e32 v111, v111
	v_exp_f32_e32 v112, v112
	v_exp_f32_e32 v113, v113
	v_exp_f32_e32 v114, v114
	v_exp_f32_e32 v115, v115
	v_exp_f32_e32 v116, v116
	v_exp_f32_e32 v117, v117
	v_exp_f32_e32 v118, v118
	v_exp_f32_e32 v119, v119
	v_exp_f32_e32 v120, v120
	v_exp_f32_e32 v121, v121
	v_exp_f32_e32 v122, v122
	v_exp_f32_e32 v123, v123
	v_exp_f32_e32 v124, v124
	v_exp_f32_e32 v125, v125
	v_exp_f32_e32 v126, v126
	v_exp_f32_e32 v127, v127
	v_exp_f32_e32 v128, v128
	v_exp_f32_e32 v129, v129
	v_exp_f32_e32 v130, v130
	v_exp_f32_e32 v131, v131
	v_exp_f32_e32 v132, v132
	v_exp_f32_e32 v133, v133
	v_exp_f32_e32 v134, v134
	v_exp_f32_e32 v135, v135
	v_exp_f32_e32 v136, v136
	v_exp_f32_e32 v137, v137
	v_exp_f32_e32 v138, v138
	v_exp_f32_e32 v139, v139
	v_exp_f32_e32 v140, v140
	v_exp_f32_e32 v141, v141
	v_pk_add_f32 v[224:225], v[224:225], v[70:71]
	v_pk_add_f32 v[226:227], v[226:227], v[106:107]
	v_pk_add_f32 v[224:225], v[224:225], v[72:73]
	v_pk_add_f32 v[226:227], v[226:227], v[108:109]
	v_pk_add_f32 v[224:225], v[224:225], v[74:75]
	v_pk_add_f32 v[226:227], v[226:227], v[110:111]
	v_pk_add_f32 v[224:225], v[224:225], v[76:77]
	v_pk_add_f32 v[226:227], v[226:227], v[112:113]
	v_pk_add_f32 v[224:225], v[224:225], v[78:79]
	v_pk_add_f32 v[226:227], v[226:227], v[114:115]
	v_pk_add_f32 v[224:225], v[224:225], v[80:81]
	v_pk_add_f32 v[226:227], v[226:227], v[116:117]
	v_pk_add_f32 v[224:225], v[224:225], v[82:83]
	v_pk_add_f32 v[226:227], v[226:227], v[118:119]
	v_pk_add_f32 v[224:225], v[224:225], v[84:85]
	v_pk_add_f32 v[226:227], v[226:227], v[120:121]
	v_pk_add_f32 v[224:225], v[224:225], v[86:87]
	v_pk_add_f32 v[226:227], v[226:227], v[122:123]
	v_pk_add_f32 v[224:225], v[224:225], v[88:89]
	v_pk_add_f32 v[226:227], v[226:227], v[124:125]
	v_pk_add_f32 v[224:225], v[224:225], v[90:91]
	v_pk_add_f32 v[226:227], v[226:227], v[126:127]
	v_pk_add_f32 v[224:225], v[224:225], v[92:93]
	v_pk_add_f32 v[226:227], v[226:227], v[128:129]
	v_pk_add_f32 v[224:225], v[224:225], v[94:95]
	v_pk_add_f32 v[226:227], v[226:227], v[130:131]
	v_pk_add_f32 v[224:225], v[224:225], v[96:97]
	v_pk_add_f32 v[226:227], v[226:227], v[132:133]
	v_pk_add_f32 v[224:225], v[224:225], v[98:99]
	v_pk_add_f32 v[226:227], v[226:227], v[134:135]
	v_pk_add_f32 v[224:225], v[224:225], v[100:101]
	v_pk_add_f32 v[226:227], v[226:227], v[136:137]
	v_pk_add_f32 v[224:225], v[224:225], v[102:103]
	v_pk_add_f32 v[226:227], v[226:227], v[138:139]
	v_pk_add_f32 v[224:225], v[224:225], v[104:105]
	v_pk_add_f32 v[226:227], v[226:227], v[140:141]
	v_cvt_pk_bf16_f32 v70, v70, v71
	v_cvt_pk_bf16_f32 v71, v72, v73
	v_cvt_pk_bf16_f32 v72, v74, v75
	v_cvt_pk_bf16_f32 v73, v76, v77
	v_cvt_pk_bf16_f32 v78, v78, v79
	v_cvt_pk_bf16_f32 v79, v80, v81
	v_cvt_pk_bf16_f32 v80, v82, v83
	v_cvt_pk_bf16_f32 v81, v84, v85
	v_cvt_pk_bf16_f32 v86, v86, v87
	v_cvt_pk_bf16_f32 v87, v88, v89
	v_cvt_pk_bf16_f32 v88, v90, v91
	v_cvt_pk_bf16_f32 v89, v92, v93
	v_cvt_pk_bf16_f32 v94, v94, v95
	v_cvt_pk_bf16_f32 v95, v96, v97
	v_cvt_pk_bf16_f32 v96, v98, v99
	v_cvt_pk_bf16_f32 v97, v100, v101
	v_cvt_pk_bf16_f32 v102, v102, v103
	v_cvt_pk_bf16_f32 v103, v104, v105
	v_mov_b32_e32 v104, 0
	v_mov_b32_e32 v105, 0
	v_cvt_pk_bf16_f32 v109, v108, v109
	v_cvt_pk_bf16_f32 v108, v106, v107
	v_mov_b32_e32 v106, 0
	v_mov_b32_e32 v107, 0
	v_cvt_pk_bf16_f32 v110, v110, v111
	v_cvt_pk_bf16_f32 v111, v112, v113
	v_cvt_pk_bf16_f32 v112, v114, v115
	v_cvt_pk_bf16_f32 v113, v116, v117
	v_cvt_pk_bf16_f32 v118, v118, v119
	v_cvt_pk_bf16_f32 v119, v120, v121
	v_cvt_pk_bf16_f32 v120, v122, v123
	v_cvt_pk_bf16_f32 v121, v124, v125
	v_cvt_pk_bf16_f32 v126, v126, v127
	v_cvt_pk_bf16_f32 v127, v128, v129
	v_cvt_pk_bf16_f32 v128, v130, v131
	v_cvt_pk_bf16_f32 v129, v132, v133
	v_cvt_pk_bf16_f32 v134, v134, v135
	v_cvt_pk_bf16_f32 v135, v136, v137
	v_cvt_pk_bf16_f32 v136, v138, v139
	v_cvt_pk_bf16_f32 v137, v140, v141
	s_add_i32 s17, s16, 0
	s_max_i32 s17, s17, 0
	s_lshl_b32 s17, s17, 11
	v_add_u32_e32 v142, s17, v230
	v_add_u32_e32 v143, s17, v231
	ds_read_b64_tr_b16 v[208:209], v142 offset:0
	ds_read_b64_tr_b16 v[210:211], v142 offset:2048
	ds_read_b64_tr_b16 v[212:213], v143 offset:0
	ds_read_b64_tr_b16 v[214:215], v143 offset:2048
	ds_read_b64_tr_b16 v[216:217], v142 offset:512
	ds_read_b64_tr_b16 v[218:219], v142 offset:2560
	ds_read_b64_tr_b16 v[220:221], v143 offset:512
	ds_read_b64_tr_b16 v[222:223], v143 offset:2560
	s_waitcnt lgkmcnt(6)
	v_mfma_f32_16x16x32_bf16 v[164:167], v[208:211], v[70:73], v[164:167]
	v_mfma_f32_16x16x32_bf16 v[168:171], v[208:211], v[106:109], v[168:171]
	s_add_i32 s17, s16, 2
	s_max_i32 s17, s17, 0
	s_lshl_b32 s17, s17, 11
	v_add_u32_e32 v144, s17, v230
	v_add_u32_e32 v145, s17, v231
	ds_read_b64_tr_b16 v[208:209], v144 offset:0
	ds_read_b64_tr_b16 v[210:211], v144 offset:2048
	s_waitcnt lgkmcnt(6)
; #define PV_RD(S, d0) do { constexpr int b_ = (d0) * 512; TRRD(S##l0, b_); TRRD(S##h0, b_ + KS_ / 2); TRRD(S##l1, b_ + KS_); TRRD(S##h1, b_ + KS_ + KS_ / 2); TRRD(S##l2, b_ + 2 * KS_); TRRD(S##h2, b_ + 2 * KS_ + KS_ / 2); TRRD(S##l3, b_ + 3 * KS_); TRRD(S##h3, b_ + 3 * KS_ + KS_ / 2); } while (0)
; #define WL(n) do { asm volatile("s_waitcnt lgkmcnt(" #n ")" ::: "memory"); SBAR(); } while (0)
; template <int NCB> __device__ __forceinline__ void pv_tile(f32x16* o, int vb, bf16x8 pa0, bf16x8 pa1, bf16x8 pa2, bf16x8 pa3) {
;     ...
;     constexpr int KS_ = NCB * 1024;
;     ...
;     s16x4 Al0, Al1, Al2, Al3, Ah0, Ah1, Ah2, Ah3, Bl0, Bl1, Bl2, Bl3, Bh0, Bh1, Bh2, Bh3;
;     PV_RD(A, 0); PV_RD(B, 1); WL(8); PV_MM(A, 0);
;     if constexpr (NCB == 4) { PV_RD(A, 2); WL(8); PV_MM(B, 1); PV_RD(B, 3); WL(8); PV_MM(A, 2); WL(0); PV_MM(B, 3); }
	v_mfma_f32_16x16x32_bf16 v[172:175], v[212:215], v[70:73], v[172:175]
	v_mfma_f32_16x16x32_bf16 v[176:179], v[212:215], v[106:109], v[176:179]
	ds_read_b64_tr_b16 v[212:213], v145 offset:0
	ds_read_b64_tr_b16 v[214:215], v145 offset:2048
	s_waitcnt lgkmcnt(6)
	v_mfma_f32_16x16x32_bf16 v[180:183], v[216:219], v[70:73], v[180:183]
	v_mfma_f32_16x16x32_bf16 v[184:187], v[216:219], v[106:109], v[184:187]
	ds_read_b64_tr_b16 v[216:217], v144 offset:512
	ds_read_b64_tr_b16 v[218:219], v144 offset:2560
	s_waitcnt lgkmcnt(6)
	v_mfma_f32_16x16x32_bf16 v[188:191], v[220:223], v[70:73], v[188:191]
	v_mfma_f32_16x16x32_bf16 v[192:195], v[220:223], v[106:109], v[192:195]
	ds_read_b64_tr_b16 v[220:221], v145 offset:512
	ds_read_b64_tr_b16 v[222:223], v145 offset:2560
	s_waitcnt lgkmcnt(6)
	v_mfma_f32_16x16x32_bf16 v[164:167], v[208:211], v[78:81], v[164:167]
	v_mfma_f32_16x16x32_bf16 v[168:171], v[208:211], v[110:113], v[168:171]
	s_add_i32 s17, s16, 4
	s_max_i32 s17, s17, 0
	s_lshl_b32 s17, s17, 11
	v_add_u32_e32 v158, s17, v230
	v_add_u32_e32 v159, s17, v231
	ds_read_b64_tr_b16 v[208:209], v158 offset:0
	ds_read_b64_tr_b16 v[210:211], v158 offset:2048
	s_waitcnt lgkmcnt(6)
	v_mfma_f32_16x16x32_bf16 v[172:175], v[212:215], v[78:81], v[172:175]
	v_mfma_f32_16x16x32_bf16 v[176:179], v[212:215], v[110:113], v[176:179]
	ds_read_b64_tr_b16 v[212:213], v159 offset:0
	ds_read_b64_tr_b16 v[214:215], v159 offset:2048
	s_waitcnt lgkmcnt(6)
	v_mfma_f32_16x16x32_bf16 v[180:183], v[216:219], v[78:81], v[180:183]
	v_mfma_f32_16x16x32_bf16 v[184:187], v[216:219], v[110:113], v[184:187]
	ds_read_b64_tr_b16 v[216:217], v158 offset:512
	ds_read_b64_tr_b16 v[218:219], v158 offset:2560
	s_waitcnt lgkmcnt(6)
	v_mfma_f32_16x16x32_bf16 v[188:191], v[220:223], v[78:81], v[188:191]
	v_mfma_f32_16x16x32_bf16 v[192:195], v[220:223], v[110:113], v[192:195]
	ds_read_b64_tr_b16 v[220:221], v159 offset:512
	ds_read_b64_tr_b16 v[222:223], v159 offset:2560
	s_waitcnt lgkmcnt(6)
	v_mfma_f32_16x16x32_bf16 v[164:167], v[208:211], v[86:89], v[164:167]
	v_mfma_f32_16x16x32_bf16 v[168:171], v[208:211], v[118:121], v[168:171]
	s_add_i32 s17, s16, 6
	s_max_i32 s17, s17, 0
	s_lshl_b32 s17, s17, 11
	v_add_u32_e32 v160, s17, v230
	v_add_u32_e32 v161, s17, v231
	ds_read_b64_tr_b16 v[208:209], v160 offset:0
	ds_read_b64_tr_b16 v[210:211], v160 offset:2048
	s_waitcnt lgkmcnt(6)
	v_mfma_f32_16x16x32_bf16 v[172:175], v[212:215], v[86:89], v[172:175]
	v_mfma_f32_16x16x32_bf16 v[176:179], v[212:215], v[118:121], v[176:179]
	ds_read_b64_tr_b16 v[212:213], v161 offset:0
	ds_read_b64_tr_b16 v[214:215], v161 offset:2048
	s_waitcnt lgkmcnt(6)
	v_mfma_f32_16x16x32_bf16 v[180:183], v[216:219], v[86:89], v[180:183]
	v_mfma_f32_16x16x32_bf16 v[184:187], v[216:219], v[118:121], v[184:187]
	ds_read_b64_tr_b16 v[216:217], v160 offset:512
	ds_read_b64_tr_b16 v[218:219], v160 offset:2560
	s_waitcnt lgkmcnt(6)
	v_mfma_f32_16x16x32_bf16 v[188:191], v[220:223], v[86:89], v[188:191]
	v_mfma_f32_16x16x32_bf16 v[192:195], v[220:223], v[118:121], v[192:195]
	ds_read_b64_tr_b16 v[220:221], v161 offset:512
	ds_read_b64_tr_b16 v[222:223], v161 offset:2560
	s_waitcnt lgkmcnt(6)
	v_mfma_f32_16x16x32_bf16 v[164:167], v[208:211], v[94:97], v[164:167]
	v_mfma_f32_16x16x32_bf16 v[168:171], v[208:211], v[126:129], v[168:171]
	s_add_i32 s17, s16, 8
	s_max_i32 s17, s17, 0
	s_lshl_b32 s17, s17, 11
	v_add_u32_e32 v204, s17, v230
	v_add_u32_e32 v207, s17, v231
	ds_read_b64_tr_b16 v[208:209], v204 offset:0
	ds_read_b64_tr_b16 v[210:211], v204 offset:2048
	s_waitcnt lgkmcnt(6)
	v_mfma_f32_16x16x32_bf16 v[172:175], v[212:215], v[94:97], v[172:175]
	v_mfma_f32_16x16x32_bf16 v[176:179], v[212:215], v[126:129], v[176:179]
	ds_read_b64_tr_b16 v[212:213], v207 offset:0
	ds_read_b64_tr_b16 v[214:215], v207 offset:2048
	s_waitcnt lgkmcnt(6)
; __device__ __forceinline__ int crow(int r, int hi) { return (r & 3) + 8 * (r >> 2) + 4 * hi; }
; __device__ __forceinline__ unsigned cvtpk(float lo, float hi) { f32x2_cv v = {lo, hi}; bf16x2_cv b = __builtin_convertvector(v, bf16x2_cv); return __builtin_bit_cast(unsigned, b); }
; __device__ __forceinline__ void finishSM(f32x16& p0, f32x16& p1, float alpha, float& l_reg, bf16x8& pa0, bf16x8& pa1, bf16x8& pa2, bf16x8& pa3) {
;     ...
;     for (int r = 0; r < 16; ++r) p1[r] = __builtin_amdgcn_exp2f(p1[r]);
;     float ps = 0;
; #pragma unroll
;     for (int r = 0; r < 16; ++r) ps += p0[r];
; #pragma unroll
;     for (int r = 0; r < 16; ++r) ps += p1[r];
;     { auto rr = __builtin_amdgcn_permlane32_swap(__float_as_uint(ps), __float_as_uint(ps), false, false);
;       ps = __uint_as_float(rr[0]) + __uint_as_float(rr[1]); }
;     l_reg = l_reg * alpha + ps;
; template <bool MLA> __device__ __forceinline__ void attn_unit(const AttnP& P, int b, int hh, int qb, LAS char* lds) {
;     ...
;     if (hi == 0) li_l[r32] = l_reg; asm volatile("s_waitcnt lgkmcnt(0)" ::: "memory");
;     bf16_t* Ow = (MLA ? P.QN + (rowbase + qlo) * 2048 + hh * 128 : P.QS + (rowbase + qlo) * 2048 + hh * 64);
; #pragma unroll
;     for (int r = 0; r < 16; ++r) { const int orow = crow(r, hi); const float rl = __builtin_amdgcn_rcpf(li_l[orow]);
; #pragma unroll
;         for (int d0 = 0; d0 < NCB; ++d0) { const float v = o[d0][r] * rl; const float vn = __shfl_xor(v, 1);
;             if ((r32 & 1) == 0) *(unsigned*)(Ow + (size_t)orow * 2048 + d0 * 32 + r32) = cvtpk(v, vn); } }
;     __syncthreads();
	v_mfma_f32_16x16x32_bf16 v[180:183], v[216:219], v[94:97], v[180:183]
	v_mfma_f32_16x16x32_bf16 v[184:187], v[216:219], v[126:129], v[184:187]
	ds_read_b64_tr_b16 v[216:217], v204 offset:512
	ds_read_b64_tr_b16 v[218:219], v204 offset:2560
	s_waitcnt lgkmcnt(6)
	v_mfma_f32_16x16x32_bf16 v[188:191], v[220:223], v[94:97], v[188:191]
	v_mfma_f32_16x16x32_bf16 v[192:195], v[220:223], v[126:129], v[192:195]
	ds_read_b64_tr_b16 v[220:221], v207 offset:512
	ds_read_b64_tr_b16 v[222:223], v207 offset:2560
	s_waitcnt lgkmcnt(6)
	v_mfma_f32_16x16x32_bf16 v[164:167], v[208:211], v[102:105], v[164:167]
	v_mfma_f32_16x16x32_bf16 v[168:171], v[208:211], v[134:137], v[168:171]
	s_waitcnt lgkmcnt(4)
	v_mfma_f32_16x16x32_bf16 v[172:175], v[212:215], v[102:105], v[172:175]
	v_mfma_f32_16x16x32_bf16 v[176:179], v[212:215], v[134:137], v[176:179]
	s_waitcnt lgkmcnt(2)
	v_mfma_f32_16x16x32_bf16 v[180:183], v[216:219], v[102:105], v[180:183]
	v_mfma_f32_16x16x32_bf16 v[184:187], v[216:219], v[134:137], v[184:187]
	s_waitcnt lgkmcnt(0)
	v_mfma_f32_16x16x32_bf16 v[188:191], v[220:223], v[102:105], v[188:191]
	v_mfma_f32_16x16x32_bf16 v[192:195], v[220:223], v[134:137], v[192:195]
	v_add_f32_e32 v224, v224, v225
	v_add_f32_e32 v226, v226, v227
	ds_bpermute_b32 v240, v236, v224
	ds_bpermute_b32 v241, v236, v226
	s_waitcnt lgkmcnt(0)
	v_add_f32_e32 v224, v224, v240
	v_add_f32_e32 v226, v226, v241
	ds_bpermute_b32 v240, v237, v224
	ds_bpermute_b32 v241, v237, v226
	s_waitcnt lgkmcnt(0)
	v_add_f32_e32 v224, v224, v240
	v_add_f32_e32 v226, v226, v241
	v_mov_b32_e32 v242, s28
	v_fma_f32 v242, v242, s29, v156
	v_exp_f32_e32 v242, v242
	s_nop 0
	v_add_f32_e32 v224, v224, v242
	v_rcp_f32_e32 v224, v224
	v_mov_b32_e32 v243, s28
	v_fma_f32 v243, v243, s29, v157
	v_exp_f32_e32 v243, v243
	s_nop 0
	v_add_f32_e32 v226, v226, v243
	v_rcp_f32_e32 v226, v226
	s_nop 7
	v_mul_f32_e32 v164, v164, v224
	v_mul_f32_e32 v165, v165, v224
	v_mul_f32_e32 v166, v166, v224
	v_mul_f32_e32 v167, v167, v224
	v_cvt_pk_bf16_f32 v164, v164, v165
	v_cvt_pk_bf16_f32 v165, v166, v167
	global_store_dwordx2 v234, v[164:165], s[50:51] offset:0
	v_mul_f32_e32 v168, v168, v226
	v_mul_f32_e32 v169, v169, v226
	v_mul_f32_e32 v170, v170, v226
	v_mul_f32_e32 v171, v171, v226
	v_cvt_pk_bf16_f32 v168, v168, v169
	v_cvt_pk_bf16_f32 v169, v170, v171
	global_store_dwordx2 v197, v[168:169], s[50:51] offset:0
	v_mul_f32_e32 v172, v172, v224
	v_mul_f32_e32 v173, v173, v224
	v_mul_f32_e32 v174, v174, v224
	v_mul_f32_e32 v175, v175, v224
	v_cvt_pk_bf16_f32 v172, v172, v173
	v_cvt_pk_bf16_f32 v173, v174, v175
	global_store_dwordx2 v234, v[172:173], s[50:51] offset:32
	v_mul_f32_e32 v176, v176, v226
	v_mul_f32_e32 v177, v177, v226
	v_mul_f32_e32 v178, v178, v226
	v_mul_f32_e32 v179, v179, v226
	v_cvt_pk_bf16_f32 v176, v176, v177
	v_cvt_pk_bf16_f32 v177, v178, v179
	global_store_dwordx2 v197, v[176:177], s[50:51] offset:32
	v_mul_f32_e32 v180, v180, v224
	v_mul_f32_e32 v181, v181, v224
	v_mul_f32_e32 v182, v182, v224
	v_mul_f32_e32 v183, v183, v224
	v_cvt_pk_bf16_f32 v180, v180, v181
	v_cvt_pk_bf16_f32 v181, v182, v183
	global_store_dwordx2 v234, v[180:181], s[50:51] offset:64
	v_mul_f32_e32 v184, v184, v226
	v_mul_f32_e32 v185, v185, v226
	v_mul_f32_e32 v186, v186, v226
	v_mul_f32_e32 v187, v187, v226
	v_cvt_pk_bf16_f32 v184, v184, v185
	v_cvt_pk_bf16_f32 v185, v186, v187
	global_store_dwordx2 v197, v[184:185], s[50:51] offset:64
	v_mul_f32_e32 v188, v188, v224
	v_mul_f32_e32 v189, v189, v224
	v_mul_f32_e32 v190, v190, v224
	v_mul_f32_e32 v191, v191, v224
	v_cvt_pk_bf16_f32 v188, v188, v189
	v_cvt_pk_bf16_f32 v189, v190, v191
	global_store_dwordx2 v234, v[188:189], s[50:51] offset:96
	v_mul_f32_e32 v192, v192, v226
	v_mul_f32_e32 v193, v193, v226
	v_mul_f32_e32 v194, v194, v226
	v_mul_f32_e32 v195, v195, v226
	v_cvt_pk_bf16_f32 v192, v192, v193
	v_cvt_pk_bf16_f32 v193, v194, v195
	global_store_dwordx2 v197, v[192:193], s[50:51] offset:96
	s_add_u32 s2, s2, s3
	s_cmp_lt_u32 s2, 0x1000
	s_cbranch_scc1 .Lsw_item
	s_waitcnt vmcnt(0) lgkmcnt(0)
	s_barrier
